# loop-back barrier moved to the loop head so the taken back-edge branch is fetched before the barrier, entry path branches past it
# baseline (speedup 1.0000x reference)
; #define LAS __attribute__((address_space(3)))
; #define MFMA32(a, b, c) __builtin_amdgcn_mfma_f32_32x32x16_bf16((a), (b), (c), 0, 0, 0)
; #define AT_ISSUE_V(jn) do { const int jc_ = (jn) < ntm1 ? (jn) : ntm1; const size_t vo_ = (size_t)jc_ * 16384; vs0 = *(const u32x4*)(bV0 + vo_ + voff); vs1 = *(const u32x4*)(bV1 + vo_ + voff); } while (0)
; #define AT_WRITE_K(jn) do { LAS unsigned char* n_ = lds + ((jn) & 1) * AT_KST; *(LAS u32x4*)(n_ + dK1) = ks0; *(LAS u32x4*)(n_ + dK2) = ks1; } while (0)
; __device__ __forceinline__ void at_pv_half(const LAS unsigned char* vp, const bf16x8 (&pf)[4], f32x16 (&O)[4], f32x16& L) {
;     bf16x8 va[8], vb[8];
; #pragma unroll
;     for (int e = 0; e < 2; ++e)
; #pragma unroll
;         for (int ks = 0; ks < 4; ++ks) va[e * 4 + ks] = *(const LAS bf16x8*)(vp + e * 32 * AT_ROWB + 32 * ks);
; #pragma unroll
;     for (int e = 0; e < 2; ++e)
; #pragma unroll
;         for (int ks = 0; ks < 4; ++ks) vb[e * 4 + ks] = *(const LAS bf16x8*)(vp + (2 + e) * 32 * AT_ROWB + 32 * ks);
;     const short one = (short)0x3F80; const bf16x8 ones = {one, one, one, one, one, one, one, one};
;     __builtin_amdgcn_sched_barrier(0);
;     __builtin_amdgcn_s_setprio(1);
; #pragma unroll
;     for (int ks = 0; ks < 4; ++ks) L = MFMA32(ones, pf[ks], L);
;     __builtin_amdgcn_sched_barrier(0);
; #pragma unroll
;     for (int ks = 0; ks < 4; ++ks) { O[0] = MFMA32(va[ks], pf[ks], O[0]); O[1] = MFMA32(va[4 + ks], pf[ks], O[1]); }
; #pragma unroll
;     for (int ks = 0; ks < 4; ++ks) { O[2] = MFMA32(vb[ks], pf[ks], O[2]); O[3] = MFMA32(vb[4 + ks], pf[ks], O[3]); }
;     __builtin_amdgcn_s_setprio(0);
; __device__ __forceinline__ void attn_item(LAS unsigned char* lds, const bf16_t* Q, const bf16_t* Kb, const bf16_t* VT, bf16_t* aout, const float* subg, float lam, float omli, float kbound, int head, int qb) {
;     ...
;         for (int j = 0; j < nt; ++j) {
;             const LAS unsigned char* stg = lds + (j & 1) * AT_KST; const LAS unsigned char* pst = lds + ((j + 1) & 1) * AT_KST; const int kbase = j * 64;
;             AT_ISSUE_V(j + 1);
;             if (j > 0 && kbase - 64 <= qmax) at_pv_half(pst + vfo, pf, O, L);
;             AT_WRITE_K(j + 1);
.LBB0_295:
	s_add_i32 s44, s45, 1
	s_bitcmp1_b32 s44, 0
	s_cselect_b32 s53, 0x4800, 0
	s_min_i32 s58, s44, s41
	s_lshl_b64 s[54:55], s[58:59], 14
	v_lshl_add_u64 v[96:97], v[208:209], 0, s[54:55]
	v_lshl_add_u64 v[98:99], v[210:211], 0, s[54:55]
	global_load_dwordx4 v[146:149], v[96:97], off
	global_load_dwordx4 v[150:153], v[98:99], off
	s_add_i32 s56, s53, 0
	s_cmp_eq_u32 s45, 0
	s_cselect_b64 s[54:55], -1, 0
	s_add_i32 s53, s1, 0xffffff81
	s_cmp_gt_i32 s53, s40
	s_cselect_b64 s[60:61], -1, 0
	s_or_b64 s[54:55], s[54:55], s[60:61]
	s_and_b64 vcc, exec, s[54:55]
	v_add_u32_e32 v184, s56, v228
	s_branch .Lmy_top1b
.Lmy_top1:
	s_barrier
	s_setprio 0
.Lmy_top1b:
	s_cbranch_vccnz .LBB0_297
	ds_read_b128 v[96:99], v184 offset:36864
	ds_read_b128 v[154:157], v184 offset:41472
	ds_read_b128 v[170:173], v184 offset:46080
	ds_read_b128 v[236:239], v184 offset:50688
	ds_read_b128 v[100:103], v184 offset:36896
	ds_read_b128 v[158:161], v184 offset:41504
	ds_read_b128 v[174:177], v184 offset:46112
	ds_read_b128 v[240:243], v184 offset:50720
	ds_read_b128 v[104:107], v184 offset:36928
	ds_read_b128 v[162:165], v184 offset:41536
	ds_read_b128 v[178:181], v184 offset:46144
	ds_read_b128 v[244:247], v184 offset:50752
	ds_read_b128 v[108:111], v184 offset:36960
	ds_read_b128 v[166:169], v184 offset:41568
	ds_read_b128 v[232:235], v184 offset:46176
	ds_read_b128 v[248:251], v184 offset:50784
	s_setprio 1
	v_mfma_f32_16x16x32_bf16 v[64:67], v[76:79], v[80:83], v[64:67]
	v_mfma_f32_16x16x32_bf16 v[64:67], v[76:79], v[88:91], v[64:67]
	v_mfma_f32_16x16x32_bf16 v[64:67], v[76:79], v[84:87], v[64:67]
	v_mfma_f32_16x16x32_bf16 v[64:67], v[76:79], v[92:95], v[64:67]
	v_add_u32_e32 v185, s56, v212
	s_waitcnt vmcnt(3)
	ds_write_b128 v185, v[142:145]
	s_waitcnt vmcnt(2)
	ds_write_b128 v185, v[138:141] offset:9216
	s_waitcnt lgkmcnt(15)
	v_mfma_f32_32x32x16_bf16 v[48:63], v[96:99], v[80:83], v[48:63]
	s_waitcnt lgkmcnt(15)
	v_mfma_f32_32x32x16_bf16 v[32:47], v[154:157], v[80:83], v[32:47]
	s_waitcnt lgkmcnt(15)
	v_mfma_f32_32x32x16_bf16 v[16:31], v[170:173], v[80:83], v[16:31]
	s_waitcnt lgkmcnt(14)
	v_mfma_f32_32x32x16_bf16 v[0:15], v[236:239], v[80:83], v[0:15]
	s_waitcnt lgkmcnt(13)
	v_mfma_f32_32x32x16_bf16 v[48:63], v[100:103], v[88:91], v[48:63]
	s_waitcnt lgkmcnt(12)
	v_mfma_f32_32x32x16_bf16 v[32:47], v[158:161], v[88:91], v[32:47]
	s_waitcnt lgkmcnt(11)
	v_mfma_f32_32x32x16_bf16 v[16:31], v[174:177], v[88:91], v[16:31]
	s_waitcnt lgkmcnt(10)
	v_mfma_f32_32x32x16_bf16 v[0:15], v[240:243], v[88:91], v[0:15]
	s_waitcnt lgkmcnt(9)
	v_mfma_f32_32x32x16_bf16 v[48:63], v[104:107], v[84:87], v[48:63]
	s_waitcnt lgkmcnt(8)
	v_mfma_f32_32x32x16_bf16 v[32:47], v[162:165], v[84:87], v[32:47]
	s_waitcnt lgkmcnt(7)
	v_mfma_f32_32x32x16_bf16 v[16:31], v[178:181], v[84:87], v[16:31]
	s_waitcnt lgkmcnt(6)
	v_mfma_f32_32x32x16_bf16 v[0:15], v[244:247], v[84:87], v[0:15]
	s_waitcnt lgkmcnt(5)
	v_mfma_f32_32x32x16_bf16 v[48:63], v[108:111], v[92:95], v[48:63]
	s_waitcnt lgkmcnt(4)
	v_mfma_f32_32x32x16_bf16 v[32:47], v[166:169], v[92:95], v[32:47]
	s_waitcnt lgkmcnt(3)
	v_mfma_f32_32x32x16_bf16 v[16:31], v[232:235], v[92:95], v[16:31]
	s_waitcnt lgkmcnt(2)
	v_mfma_f32_32x32x16_bf16 v[0:15], v[248:251], v[92:95], v[0:15]
	s_setprio 0
	s_branch .Lmy_wj1

; #define LAS __attribute__((address_space(3)))
; #define AT_ISSUE_V(jn) do { const int jc_ = (jn) < ntm1 ? (jn) : ntm1; const size_t vo_ = (size_t)jc_ * 16384; vs0 = *(const u32x4*)(bV0 + vo_ + voff); vs1 = *(const u32x4*)(bV1 + vo_ + voff); } while (0)
; #define AT_WRITE_V(jn) do { LAS unsigned char* n_ = lds + ((jn) & 1) * AT_KST; *(LAS u32x4*)(n_ + dV0) = vs0; *(LAS u32x4*)(n_ + dV1) = vs1; } while (0)
; __device__ __forceinline__ void attn_item(LAS unsigned char* lds, const bf16_t* Q, const bf16_t* Kb, const bf16_t* VT, bf16_t* aout, const float* subg, float lam, float omli, float kbound, int head, int qb) {
;     ...
;             const LAS unsigned char* stg = lds + (j & 1) * AT_KST; const LAS unsigned char* pst = lds + ((j + 1) & 1) * AT_KST; const int kbase = j * 64;
;             AT_ISSUE_V(j + 1);
;             if (j > 0 && kbase - 64 <= qmax) at_pv_half(pst + vfo, pf, O, L);
;     ...
;             AT_WRITE_V(j + 1);
;             __syncthreads();
;             __builtin_amdgcn_s_setprio(0);
.LBB0_304:
	s_setprio 3
	s_waitcnt vmcnt(3)
	ds_write_b128 v232, v[146:149] offset:36864
	s_waitcnt vmcnt(2)
	ds_write_b128 v232, v[150:153] offset:46080
	s_waitcnt lgkmcnt(0)
	s_add_i32 s1, s1, 64
	s_cmp_eq_u32 s0, s44
	s_cbranch_scc1 .Lmy_exit1
	s_mov_b32 s45, s44
	s_add_i32 s44, s45, 1
	s_bitcmp1_b32 s44, 0
	s_cselect_b32 s53, 0x4800, 0
	s_min_i32 s58, s44, s41
	s_lshl_b64 s[54:55], s[58:59], 14
	v_lshl_add_u64 v[96:97], v[208:209], 0, s[54:55]
	v_lshl_add_u64 v[98:99], v[210:211], 0, s[54:55]
	global_load_dwordx4 v[146:149], v[96:97], off
	global_load_dwordx4 v[150:153], v[98:99], off
	s_add_i32 s56, s53, 0
	s_cmp_eq_u32 s45, 0
	s_cselect_b64 s[54:55], -1, 0
	s_add_i32 s53, s1, 0xffffff81
	s_cmp_gt_i32 s53, s40
	s_cselect_b64 s[60:61], -1, 0
	s_or_b64 s[54:55], s[54:55], s[60:61]
	s_and_b64 vcc, exec, s[54:55]
	v_add_u32_e32 v184, s56, v228
	s_branch .Lmy_top1

; #define LAS __attribute__((address_space(3)))
; __device__ __forceinline__ void attn_item(LAS unsigned char* lds, const bf16_t* Q, const bf16_t* Kb, const bf16_t* VT, bf16_t* aout, const float* subg, float lam, float omli, float kbound, int head, int qb) {
;     ...
;         for (int j = 0; j < nt; ++j) {
;             const LAS unsigned char* stg = lds + (j & 1) * AT_KST; const int kbase = j * 64; const bool act = kbase <= qmax;
;             __builtin_amdgcn_s_setprio(3);
;             { const int jc_ = (j + 1) < ntm1 ? (j + 1) : ntm1; const size_t vo_ = (size_t)jc_ * 16384; const char* pga = bV0 + vo_ + voff; const char* pgb = bV1 + vo_ + voff;
;               at_qk_half(online, act, stg + kfo, vs0, vs1, pga, pgb, qf, q, q0, kbase, hh, mrun, O, L, pf); }
.LBB0_313:
	s_bitcmp1_b32 s53, 0
	s_cselect_b32 s0, 0x4800, 0
	s_add_i32 s54, s0, 0
	s_sub_i32 s55, s45, 63
	s_cmp_le_i32 s55, s40
	s_cselect_b64 s[0:1], -1, 0
	s_add_i32 s56, s53, 1
	s_min_i32 s58, s56, s41
	s_lshl_b64 s[60:61], s[58:59], 14
	s_cmp_gt_i32 s55, s40
	s_setprio 3
	v_lshl_add_u64 v[100:101], v[208:209], 0, s[60:61]
	v_lshl_add_u64 v[102:103], v[210:211], 0, s[60:61]
	v_add_u32_e32 v104, s54, v229
	s_branch .Lmy_top3b
.Lmy_top3:
	s_barrier
	s_setprio 3

; #define LAS __attribute__((address_space(3)))
; #define AT_ISSUE_K(jn) do { const int jc_ = (jn) < ntm1 ? (jn) : ntm1; const size_t ko_ = (size_t)jc_ * 8192; ks0 = *(const u32x4*)(bK1 + ko_ + koff); ks1 = *(const u32x4*)(bK2 + ko_ + koff); } while (0)
; #define AT_WRITE_K(jn) do { LAS unsigned char* n_ = lds + ((jn) & 1) * AT_KST; *(LAS u32x4*)(n_ + dK1) = ks0; *(LAS u32x4*)(n_ + dK2) = ks1; } while (0)
; #define AT_WRITE_V(jn) do { LAS unsigned char* n_ = lds + ((jn) & 1) * AT_KST; *(LAS u32x4*)(n_ + dV0) = vs0; *(LAS u32x4*)(n_ + dV1) = vs1; } while (0)
; __device__ __forceinline__ void attn_item(LAS unsigned char* lds, const bf16_t* Q, const bf16_t* Kb, const bf16_t* VT, bf16_t* aout, const float* subg, float lam, float omli, float kbound, int head, int qb) {
;     ...
;         for (int j = 0; j < nt; ++j) {
;             const LAS unsigned char* stg = lds + (j & 1) * AT_KST; const int kbase = j * 64; const bool act = kbase <= qmax;
;             __builtin_amdgcn_s_setprio(3);
;             { const int jc_ = (j + 1) < ntm1 ? (j + 1) : ntm1; const size_t vo_ = (size_t)jc_ * 16384; const char* pga = bV0 + vo_ + voff; const char* pgb = bV1 + vo_ + voff;
;               at_qk_half(online, act, stg + kfo, vs0, vs1, pga, pgb, qf, q, q0, kbase, hh, mrun, O, L, pf); }
;             __builtin_amdgcn_s_setprio(3);
;             AT_WRITE_K(j + 1);
;             __syncthreads();
;             __builtin_amdgcn_s_setprio(0);
;             AT_ISSUE_K(j + 2);
;             if (act) at_pv_half(stg + vfo, pf, O, L);
;             AT_WRITE_V(j + 1);
;             __syncthreads();
;         }
.Lmy_wj3:
	s_add_i32 s45, s45, 64
	s_cmp_eq_u32 s44, s56
	s_cbranch_scc1 .Lmy_exit3
	s_mov_b32 s53, s56
	s_bitcmp1_b32 s53, 0
	s_cselect_b32 s0, 0x4800, 0
	s_add_i32 s54, s0, 0
	s_sub_i32 s55, s45, 63
	s_cmp_le_i32 s55, s40
	s_cselect_b64 s[0:1], -1, 0
	s_add_i32 s56, s53, 1
	s_min_i32 s58, s56, s41
	s_lshl_b64 s[60:61], s[58:59], 14
	s_cmp_gt_i32 s55, s40
	v_lshl_add_u64 v[100:101], v[208:209], 0, s[60:61]
	v_lshl_add_u64 v[102:103], v[210:211], 0, s[60:61]
	v_add_u32_e32 v104, s54, v229
	s_waitcnt lgkmcnt(0)
	s_branch .Lmy_top3

; #define LAS __attribute__((address_space(3)))
; #define MFMA32(a, b, c) __builtin_amdgcn_mfma_f32_32x32x16_bf16((a), (b), (c), 0, 0, 0)
; #define AT_ISSUE_V(jn) do { const int jc_ = (jn) < ntm1 ? (jn) : ntm1; const size_t vo_ = (size_t)jc_ * 16384; vs0 = *(const u32x4*)(bV0 + vo_ + voff); vs1 = *(const u32x4*)(bV1 + vo_ + voff); } while (0)
; #define AT_WRITE_K(jn) do { LAS unsigned char* n_ = lds + ((jn) & 1) * AT_KST; *(LAS u32x4*)(n_ + dK1) = ks0; *(LAS u32x4*)(n_ + dK2) = ks1; } while (0)
; __device__ __forceinline__ void at_pv_half(const LAS unsigned char* vp, const bf16x8 (&pf)[4], f32x16 (&O)[4], f32x16& L) {
;     bf16x8 va[8], vb[8];
; #pragma unroll
;     for (int e = 0; e < 2; ++e)
; #pragma unroll
;         for (int ks = 0; ks < 4; ++ks) va[e * 4 + ks] = *(const LAS bf16x8*)(vp + e * 32 * AT_ROWB + 32 * ks);
; #pragma unroll
;     for (int e = 0; e < 2; ++e)
; #pragma unroll
;         for (int ks = 0; ks < 4; ++ks) vb[e * 4 + ks] = *(const LAS bf16x8*)(vp + (2 + e) * 32 * AT_ROWB + 32 * ks);
;     const short one = (short)0x3F80; const bf16x8 ones = {one, one, one, one, one, one, one, one};
;     __builtin_amdgcn_sched_barrier(0);
;     __builtin_amdgcn_s_setprio(1);
; #pragma unroll
;     for (int ks = 0; ks < 4; ++ks) L = MFMA32(ones, pf[ks], L);
;     __builtin_amdgcn_sched_barrier(0);
; #pragma unroll
;     for (int ks = 0; ks < 4; ++ks) { O[0] = MFMA32(va[ks], pf[ks], O[0]); O[1] = MFMA32(va[4 + ks], pf[ks], O[1]); }
; #pragma unroll
;     for (int ks = 0; ks < 4; ++ks) { O[2] = MFMA32(vb[ks], pf[ks], O[2]); O[3] = MFMA32(vb[4 + ks], pf[ks], O[3]); }
;     __builtin_amdgcn_s_setprio(0);
; __device__ __forceinline__ void attn_item(LAS unsigned char* lds, const bf16_t* Q, const bf16_t* Kb, const bf16_t* VT, bf16_t* aout, const float* subg, float lam, float omli, float kbound, int head, int qb) {
;     ...
;         for (int j = 0; j < nt; ++j) {
;             const LAS unsigned char* stg = lds + (j & 1) * AT_KST; const LAS unsigned char* pst = lds + ((j + 1) & 1) * AT_KST; const int kbase = j * 64;
;             AT_ISSUE_V(j + 1);
;             if (j > 0 && kbase - 64 <= qmax) at_pv_half(pst + vfo, pf, O, L);
;             AT_WRITE_K(j + 1);
.LBB0_333:
	s_add_i32 s38, s39, 1
	s_bitcmp1_b32 s38, 0
	s_cselect_b32 s42, 0x4800, 0
	s_min_i32 s58, s38, s22
	s_lshl_b64 s[40:41], s[58:59], 14
	v_lshl_add_u64 v[96:97], v[208:209], 0, s[40:41]
	v_lshl_add_u64 v[98:99], v[210:211], 0, s[40:41]
	global_load_dwordx4 v[146:149], v[96:97], off
	global_load_dwordx4 v[150:153], v[98:99], off
	s_add_i32 s40, s42, 0
	s_cmp_eq_u32 s39, 0
	s_cselect_b64 s[42:43], -1, 0
	s_add_i32 s41, s1, 0xffffff81
	s_cmp_gt_i32 s41, s21
	s_cselect_b64 s[44:45], -1, 0
	s_or_b64 s[42:43], s[42:43], s[44:45]
	s_and_b64 vcc, exec, s[42:43]
	v_add_u32_e32 v244, s40, v228
	s_branch .Lmy_top4b
.Lmy_top4:
	s_barrier
	s_setprio 0
.Lmy_top4b:
	s_cbranch_vccnz .LBB0_335
	ds_read_b128 v[96:99], v244 offset:36864
	ds_read_b128 v[154:157], v244 offset:41472
	ds_read_b128 v[170:173], v244 offset:46080
	ds_read_b128 v[232:235], v244 offset:50688
	ds_read_b128 v[100:103], v244 offset:36896
	ds_read_b128 v[158:161], v244 offset:41504
	ds_read_b128 v[174:177], v244 offset:46112
	ds_read_b128 v[236:239], v244 offset:50720
	ds_read_b128 v[104:107], v244 offset:36928
	ds_read_b128 v[162:165], v244 offset:41536
	ds_read_b128 v[178:181], v244 offset:46144
	ds_read_b128 v[240:243], v244 offset:50752
	ds_read_b128 v[108:111], v244 offset:36960
	ds_read_b128 v[166:169], v244 offset:41568
	ds_read_b128 v[184:187], v244 offset:46176
	ds_read_b128 v[244:247], v244 offset:50784
	s_setprio 1
	v_mfma_f32_16x16x32_bf16 v[64:67], v[76:79], v[80:83], v[64:67]
	v_mfma_f32_16x16x32_bf16 v[64:67], v[76:79], v[88:91], v[64:67]
	v_mfma_f32_16x16x32_bf16 v[64:67], v[76:79], v[84:87], v[64:67]
	v_mfma_f32_16x16x32_bf16 v[64:67], v[76:79], v[92:95], v[64:67]
	v_add_u32_e32 v249, s40, v212
	s_waitcnt vmcnt(3)
	ds_write_b128 v249, v[142:145]
	s_waitcnt vmcnt(2)
	ds_write_b128 v249, v[138:141] offset:9216
	s_waitcnt lgkmcnt(15)
	v_mfma_f32_32x32x16_bf16 v[48:63], v[96:99], v[80:83], v[48:63]
	s_waitcnt lgkmcnt(15)
	v_mfma_f32_32x32x16_bf16 v[32:47], v[154:157], v[80:83], v[32:47]
	s_waitcnt lgkmcnt(15)
	v_mfma_f32_32x32x16_bf16 v[16:31], v[170:173], v[80:83], v[16:31]
	s_waitcnt lgkmcnt(14)
	v_mfma_f32_32x32x16_bf16 v[0:15], v[232:235], v[80:83], v[0:15]
	s_waitcnt lgkmcnt(13)
	v_mfma_f32_32x32x16_bf16 v[48:63], v[100:103], v[88:91], v[48:63]
	s_waitcnt lgkmcnt(12)
	v_mfma_f32_32x32x16_bf16 v[32:47], v[158:161], v[88:91], v[32:47]
	s_waitcnt lgkmcnt(11)
	v_mfma_f32_32x32x16_bf16 v[16:31], v[174:177], v[88:91], v[16:31]
	s_waitcnt lgkmcnt(10)
	v_mfma_f32_32x32x16_bf16 v[0:15], v[236:239], v[88:91], v[0:15]
	s_waitcnt lgkmcnt(9)
	v_mfma_f32_32x32x16_bf16 v[48:63], v[104:107], v[84:87], v[48:63]
	s_waitcnt lgkmcnt(8)
	v_mfma_f32_32x32x16_bf16 v[32:47], v[162:165], v[84:87], v[32:47]
	s_waitcnt lgkmcnt(7)
	v_mfma_f32_32x32x16_bf16 v[16:31], v[178:181], v[84:87], v[16:31]
	s_waitcnt lgkmcnt(6)
	v_mfma_f32_32x32x16_bf16 v[0:15], v[240:243], v[84:87], v[0:15]
	s_waitcnt lgkmcnt(5)
	v_mfma_f32_32x32x16_bf16 v[48:63], v[108:111], v[92:95], v[48:63]
	s_waitcnt lgkmcnt(4)
	v_mfma_f32_32x32x16_bf16 v[32:47], v[166:169], v[92:95], v[32:47]
	s_waitcnt lgkmcnt(3)
	v_mfma_f32_32x32x16_bf16 v[16:31], v[184:187], v[92:95], v[16:31]
	s_waitcnt lgkmcnt(2)
	v_mfma_f32_32x32x16_bf16 v[0:15], v[244:247], v[92:95], v[0:15]
	s_setprio 0
	s_branch .Lmy_wj4

; #define LAS __attribute__((address_space(3)))
; #define AT_ISSUE_V(jn) do { const int jc_ = (jn) < ntm1 ? (jn) : ntm1; const size_t vo_ = (size_t)jc_ * 16384; vs0 = *(const u32x4*)(bV0 + vo_ + voff); vs1 = *(const u32x4*)(bV1 + vo_ + voff); } while (0)
; #define AT_WRITE_V(jn) do { LAS unsigned char* n_ = lds + ((jn) & 1) * AT_KST; *(LAS u32x4*)(n_ + dV0) = vs0; *(LAS u32x4*)(n_ + dV1) = vs1; } while (0)
; __device__ __forceinline__ void attn_item(LAS unsigned char* lds, const bf16_t* Q, const bf16_t* Kb, const bf16_t* VT, bf16_t* aout, const float* subg, float lam, float omli, float kbound, int head, int qb) {
;     ...
;             const LAS unsigned char* stg = lds + (j & 1) * AT_KST; const LAS unsigned char* pst = lds + ((j + 1) & 1) * AT_KST; const int kbase = j * 64;
;             AT_ISSUE_V(j + 1);
;             if (j > 0 && kbase - 64 <= qmax) at_pv_half(pst + vfo, pf, O, L);
;     ...
;             AT_WRITE_V(j + 1);
;             __syncthreads();
;             __builtin_amdgcn_s_setprio(0);
.LBB0_342:
	s_setprio 3
	s_waitcnt vmcnt(3)
	ds_write_b128 v232, v[146:149] offset:36864
	s_waitcnt vmcnt(2)
	ds_write_b128 v232, v[150:153] offset:46080
	s_waitcnt lgkmcnt(0)
	s_add_i32 s1, s1, 64
	s_cmp_eq_u32 s0, s38
	s_cbranch_scc1 .Lmy_exit4
	s_mov_b32 s39, s38
	s_add_i32 s38, s39, 1
	s_bitcmp1_b32 s38, 0
	s_cselect_b32 s42, 0x4800, 0
	s_min_i32 s58, s38, s22
	s_lshl_b64 s[40:41], s[58:59], 14
	v_lshl_add_u64 v[96:97], v[208:209], 0, s[40:41]
	v_lshl_add_u64 v[98:99], v[210:211], 0, s[40:41]
	global_load_dwordx4 v[146:149], v[96:97], off
	global_load_dwordx4 v[150:153], v[98:99], off
	s_add_i32 s40, s42, 0
	s_cmp_eq_u32 s39, 0
	s_cselect_b64 s[42:43], -1, 0
	s_add_i32 s41, s1, 0xffffff81
	s_cmp_gt_i32 s41, s21
	s_cselect_b64 s[44:45], -1, 0
	s_or_b64 s[42:43], s[42:43], s[44:45]
	s_and_b64 vcc, exec, s[42:43]
	v_add_u32_e32 v244, s40, v228
	s_branch .Lmy_top4

; #define LAS __attribute__((address_space(3)))
; __device__ __forceinline__ void attn_item(LAS unsigned char* lds, const bf16_t* Q, const bf16_t* Kb, const bf16_t* VT, bf16_t* aout, const float* subg, float lam, float omli, float kbound, int head, int qb) {
;     ...
;         for (int j = 0; j < nt; ++j) {
;             const LAS unsigned char* stg = lds + (j & 1) * AT_KST; const int kbase = j * 64; const bool act = kbase <= qmax;
;             __builtin_amdgcn_s_setprio(3);
;             { const int jc_ = (j + 1) < ntm1 ? (j + 1) : ntm1; const size_t vo_ = (size_t)jc_ * 16384; const char* pga = bV0 + vo_ + voff; const char* pgb = bV1 + vo_ + voff;
;               at_qk_half(online, act, stg + kfo, vs0, vs1, pga, pgb, qf, q, q0, kbase, hh, mrun, O, L, pf); }
.LBB0_351:
	s_bitcmp1_b32 s38, 0
	s_cselect_b32 s0, 0x4800, 0
	s_add_i32 s40, s0, 0
	s_sub_i32 s41, s20, 63
	s_cmp_le_i32 s41, s21
	s_cselect_b64 s[0:1], -1, 0
	s_add_i32 s39, s38, 1
	s_min_i32 s58, s39, s22
	s_lshl_b64 s[42:43], s[58:59], 14
	s_cmp_gt_i32 s41, s21
	s_setprio 3
	v_lshl_add_u64 v[100:101], v[208:209], 0, s[42:43]
	v_lshl_add_u64 v[102:103], v[210:211], 0, s[42:43]
	v_add_u32_e32 v104, s40, v229
	s_branch .Lmy_top6b

; #define LAS __attribute__((address_space(3)))
; #define AT_ISSUE_K(jn) do { const int jc_ = (jn) < ntm1 ? (jn) : ntm1; const size_t ko_ = (size_t)jc_ * 8192; ks0 = *(const u32x4*)(bK1 + ko_ + koff); ks1 = *(const u32x4*)(bK2 + ko_ + koff); } while (0)
; #define AT_WRITE_K(jn) do { LAS unsigned char* n_ = lds + ((jn) & 1) * AT_KST; *(LAS u32x4*)(n_ + dK1) = ks0; *(LAS u32x4*)(n_ + dK2) = ks1; } while (0)
; #define AT_WRITE_V(jn) do { LAS unsigned char* n_ = lds + ((jn) & 1) * AT_KST; *(LAS u32x4*)(n_ + dV0) = vs0; *(LAS u32x4*)(n_ + dV1) = vs1; } while (0)
; __device__ __forceinline__ void attn_item(LAS unsigned char* lds, const bf16_t* Q, const bf16_t* Kb, const bf16_t* VT, bf16_t* aout, const float* subg, float lam, float omli, float kbound, int head, int qb) {
;     ...
;         for (int j = 0; j < nt; ++j) {
;             const LAS unsigned char* stg = lds + (j & 1) * AT_KST; const int kbase = j * 64; const bool act = kbase <= qmax;
;             __builtin_amdgcn_s_setprio(3);
;             { const int jc_ = (j + 1) < ntm1 ? (j + 1) : ntm1; const size_t vo_ = (size_t)jc_ * 16384; const char* pga = bV0 + vo_ + voff; const char* pgb = bV1 + vo_ + voff;
;               at_qk_half(online, act, stg + kfo, vs0, vs1, pga, pgb, qf, q, q0, kbase, hh, mrun, O, L, pf); }
;             __builtin_amdgcn_s_setprio(3);
;             AT_WRITE_K(j + 1);
;             __syncthreads();
;             __builtin_amdgcn_s_setprio(0);
;             AT_ISSUE_K(j + 2);
;             if (act) at_pv_half(stg + vfo, pf, O, L);
;             AT_WRITE_V(j + 1);
;             __syncthreads();
;         }
.Lmy_wj6:
	s_add_i32 s20, s20, 64
	s_cmp_eq_u32 s19, s39
	s_cbranch_scc1 .Lmy_exit6
	s_mov_b32 s38, s39
	s_bitcmp1_b32 s38, 0
	s_cselect_b32 s0, 0x4800, 0
	s_add_i32 s40, s0, 0
	s_sub_i32 s41, s20, 63
	s_cmp_le_i32 s41, s21
	s_cselect_b64 s[0:1], -1, 0
	s_add_i32 s39, s38, 1
	s_min_i32 s58, s39, s22
	s_lshl_b64 s[42:43], s[58:59], 14
	s_cmp_gt_i32 s41, s21
	v_lshl_add_u64 v[100:101], v[208:209], 0, s[42:43]
	v_lshl_add_u64 v[102:103], v[210:211], 0, s[42:43]
	v_add_u32_e32 v104, s40, v229
	s_waitcnt lgkmcnt(0)
	s_branch .Lmy_top6
